# LDS bank conflicts: attention K-tile chunk swizzle changed from row&7 to (row>>1)&7 in writers and readers (conflict-free under the ds_read_b128 lane grouping)
# speedup vs baseline: 1.0056x; 1.0056x over previous
; __device__ __forceinline__ int v_st(int k, int c) { const int kk = (k & ~0xC) | ((k & 4) << 1) | ((k & 8) >> 1); return ((kk >> 3) * 4 + (c >> 5)) * 512 + ((kk & 7) * 32 + (c & 31)) * 2; }
; __device__ __forceinline__ int v_rd_base(int lane) { return ((lane & 3) << 3) | (((lane >> 2) & 3) << 6) | (((lane >> 4) & 1) << 5) | (((lane >> 5) & 1) << 8); }
; template <int DQK, int DK1, int LDQ, int LDK, int LDKR, int LDV, int NQL, int SDEPTH>
; __device__ __forceinline__ void attn_core(const AttnArgs& a, char* lds, f32x16 (&o)[4]) {
;     ...
;     { const bf16_t* Qw = a.Q + (long)(wid * 32 + r32) * LDQ + hi * 8;
; #pragma unroll
;       for (int d0 = 0; d0 < NQR; ++d0) qr[d0] = *(const bf16x8*)(Qw + d0 * 16);
; #pragma unroll
;       for (int d0 = NQR; d0 < ND0; ++d0) *(bf16x8*)(QL + (d0 - NQR) * 8192) = *(const bf16x8*)(Qw + d0 * 16); }
;     const int sr = tid >> 4, sc = (tid & 15) * 8, vst0 = v_st(sr, sc), vst1 = v_st(32 + sr, sc);
;     const int vb0 = (int)(uintptr_t)V_lds + v_rd_base(lane);
;     const bf16_t* kptr[KCH]; int kld[KCH], kwo[KCH];
; #pragma unroll
;     for (int c = 0; c < KCH; ++c) { const int idx = tid + c * 512, kr_ = idx / CPR, kc = (idx % CPR) * 8;
;         if (kc < DK1) { kptr[c] = a.Kn + (long)kr_ * LDK + kc; kld[c] = LDK; } else { kptr[c] = a.Kr + (long)kr_ * LDKR + (kc - DK1); kld[c] = LDKR; }
;         kwo[c] = kr_ * KP + ((kc * 2) ^ ((kr_ & 7) << 4)); }
;     struct { bf16x8 vs0, vs1, ks[KCH]; } sr_[SDEPTH];
;     int kb[4];
; #pragma unroll
;     for (int m = 0; m < 4; ++m) kb[m] = r32 * KP + ((m * 32 + hi * 16) ^ ((r32 & 7) << 4));
.LBB0_170:
	v_mov_b32_e32 v14, v159
	s_xor_b64 s[94:95], s[14:15], -1
	s_lshl_b64 s[14:15], s[12:13], 1
	s_add_u32 s12, s87, s14
	v_ashrrev_i32_e32 v0, 31, v14
	v_lshrrev_b32_e32 v0, 29, v0
	s_addc_u32 s13, s68, s15
	v_add_u32_e32 v0, v14, v0
	s_add_u32 s14, s28, s14
	v_ashrrev_i32_e32 v16, 3, v0
	v_and_b32_e32 v0, -8, v0
	s_addc_u32 s15, s29, s15
	v_sub_u32_e32 v17, v14, v0
	v_ashrrev_i32_e32 v164, 4, v14
	v_lshlrev_b32_e32 v0, 3, v17
	v_mov_b64_e32 v[2:3], s[14:15]
	v_mad_i64_i32 v[2:3], s[14:15], v16, s9, v[2:3]
	v_ashrrev_i32_e32 v1, 31, v0
	v_ashrrev_i32_e32 v165, 31, v164
	v_lshlrev_b32_e32 v15, 3, v14
	v_lshl_add_u64 v[166:167], v[0:1], 1, v[2:3]
	v_lshl_add_u64 v[0:1], v[164:165], 0, s[18:19]
	v_mov_b64_e32 v[50:51], s[20:21]
	v_and_b32_e32 v4, 0x78, v15
	v_mad_u64_u32 v[2:3], s[14:15], v0, s9, v[50:51]
	v_mad_i32_i24 v3, v1, s9, v3
	v_lshlrev_b32_e32 v48, 1, v4
	v_mov_b32_e32 v49, v97
	v_lshl_add_u64 v[168:169], v[164:165], 0, 32
	v_lshl_add_u64 v[0:1], v[2:3], 0, v[48:49]
	v_lshl_add_u64 v[2:3], v[168:169], 0, s[18:19]
	v_mad_u64_u32 v[4:5], s[14:15], v2, s9, v[50:51]
	v_mad_i32_i24 v5, v3, s9, v5
	v_lshl_add_u64 v[4:5], v[4:5], 0, v[48:49]
	global_load_dwordx4 v[0:3], v[0:1], off
	s_nop 0
	global_load_dwordx4 v[4:7], v[4:5], off
	v_ashrrev_i32_e32 v12, 1, v14
	v_lshl_add_u64 v[8:9], v[166:167], 0, s[22:23]
	v_bfi_b32 v18, s33, v12, v14
	v_mov_b64_e32 v[12:13], s[12:13]
	global_load_dwordx4 v[8:11], v[8:9], off
	v_mad_i64_i32 v[12:13], s[12:13], v18, s9, v[12:13]
	v_lshrrev_b32_e32 v18, 1, v14
	v_and_b32_e32 v96, 16, v18
	v_lshl_add_u64 v[12:13], v[12:13], 0, v[96:97]
	global_load_dwordx4 v[110:113], v[12:13], off
	global_load_dwordx4 v[106:109], v[12:13], off offset:32
	global_load_dwordx4 v[102:105], v[12:13], off offset:64
	global_load_dwordx4 v[98:101], v[12:13], off offset:96
	v_and_b32_e32 v18, 0xfffff0, v164
	v_lshlrev_b32_e32 v19, 1, v164
	v_lshrrev_b32_e32 v20, 1, v164
	v_and_b32_e32 v21, 3, v164
	v_add_u32_e32 v22, 32, v164
	v_and_or_b32 v18, v19, 8, v18
	v_and_or_b32 v19, v20, 4, v21
	v_and_b32_e32 v20, 0xfffff0, v22
	v_lshlrev_b32_e32 v21, 1, v22
	v_bfe_u32 v15, v15, 5, 2
	v_lshrrev_b32_e32 v18, 1, v18
	v_and_or_b32 v20, v21, 8, v20
	v_and_b32_e32 v68, 31, v14
	v_lshlrev_b32_e32 v52, 4, v14
	v_or_b32_e32 v12, v18, v15
	v_lshrrev_b32_e32 v13, 1, v20
	v_lshlrev_b32_e32 v53, 7, v68
	v_lshrrev_b32_e32 v54, 1, v52
	v_and_b32_e32 v54, 0x70, v54
	v_and_b32_e32 v23, 48, v52
	v_lshlrev_b32_e32 v19, 6, v19
	v_lshlrev_b32_e32 v12, 9, v12
	v_or_b32_e32 v13, v13, v15
	v_bitop3_b32 v22, v96, v53, v54 bitop3:0xde
	v_lshlrev_b32_e32 v18, 7, v16
	v_lshrrev_b32_e32 v243, 1, v16
	v_bitop3_b32 v15, v243, v17, 7 bitop3:0x6c
	v_lshlrev_b32_e32 v13, 9, v13
	v_or3_b32 v12, v12, v19, v23
	v_lshl_add_u32 v15, v15, 4, v18
	v_or3_b32 v13, v13, v19, v23
	v_add_u32_e32 v181, 0, v12
	v_add_u32_e32 v186, 0, v22
	v_add_u32_e32 v182, 0, v15
	v_add_u32_e32 v184, 0, v13
	s_waitcnt vmcnt(0)
	v_and_b32_e32 v69, 63, v14
	v_lshl_add_u64 v[64:65], v[164:165], 0, s[88:89]
	v_mad_u64_u32 v[66:67], s[12:13], v64, s9, v[50:51]
	v_mad_i32_i24 v67, v65, s9, v67
	v_lshl_add_u64 v[60:61], v[166:167], 0, s[78:79]
	v_lshl_add_u64 v[64:65], v[66:67], 0, v[48:49]
	s_cmp_lg_u32 0, -1
	s_cselect_b32 s14, 0, 0
	s_waitcnt vmcnt(0)
	ds_write_b128 v181, v[0:3]
	s_waitcnt vmcnt(5)
	ds_write_b128 v184, v[4:7]
	s_waitcnt vmcnt(4)
	ds_write_b128 v182, v[8:11] offset:32768
	s_waitcnt lgkmcnt(0)
	s_barrier
; #define SLOAD(i, j) do { const long rb_ = KROW(j); sr_[i].vs0 = *(const bf16x8*)(a.V + (rb_ + sr) * LDV + sc); sr_[i].vs1 = *(const bf16x8*)(a.V + (rb_ + 32 + sr) * LDV + sc); \
;     _Pragma("unroll") for (int c_ = 0; c_ < KCH; ++c_) sr_[i].ks[c_] = *(const bf16x8*)(kptr[c_] + rb_ * kld[c_]); } while (0)
; #define SWRITE(b, i) do { *(bf16x8*)(V_lds + (b) * SHM_V + vst0) = sr_[i].vs0; *(bf16x8*)(V_lds + (b) * SHM_V + vst1) = sr_[i].vs1; \
;     _Pragma("unroll") for (int c_ = 0; c_ < KCH; ++c_) *(bf16x8*)(K_lds + (b) * SHM_K + kwo[c_]) = sr_[i].ks[c_]; } while (0)
; __device__ __forceinline__ void partialSM(f32x16& p0, f32x16& p1, float& m_reg, float& mn, float& alpha, const float C, const float thr) {
;     float pmax = p0[0];
; #pragma unroll
;     for (int r = 1; r < 16; ++r) pmax = fmaxf(pmax, p0[r]);
; #pragma unroll
;     for (int r = 0; r < 16; ++r) pmax = fmaxf(pmax, p1[r]);
;     { auto rr = __builtin_amdgcn_permlane32_swap(__float_as_uint(pmax), __float_as_uint(pmax), false, false);
;       pmax = fmaxf(__uint_as_float(rr[0]), __uint_as_float(rr[1])); }
;     if (__builtin_expect(__all(pmax - m_reg <= thr), 1)) { mn = m_reg; alpha = 1.f; }
;     else { mn = fmaxf(m_reg, pmax); alpha = __builtin_amdgcn_exp2f((m_reg - mn) * C); m_reg = mn; }
;     const float mnC = -mn * C;
; #pragma unroll
;     for (int r = 0; r < 16; ++r) p0[r] = fmaf(p0[r], C, mnC);
; #pragma unroll
;     for (int r = 0; r < 16; ++r) p1[r] = fmaf(p1[r], C, mnC);
; #pragma unroll
;     for (int r = 0; r < 16; ++r) p0[r] = __builtin_amdgcn_exp2f(p0[r]);
; template <int DQK, int DK1, int LDQ, int LDK, int LDKR, int LDV, int NQL, int SDEPTH>
; __device__ __forceinline__ void attn_core(const AttnArgs& a, char* lds, f32x16 (&o)[4]) {
;     ...
;     f32x16 pA0, pA1, pB0, pB1; float mnA, mnB, alA, alB; bf16x8 pa0, pa1, pa2, pa3; const int NT = a.NT;
;     constexpr int SE = 0, SO = SDEPTH - 1;
;     SLOAD(SE, 0); asm volatile("s_waitcnt vmcnt(0)" ::: "memory"); SWRITE(0, SE); __syncthreads();
;     QKT(pA0, pA1, K_lds); partialSM(pA0, pA1, m_reg, mnA, alA, a.C, a.thr);
;     SLOAD(SO, 1); if (SDEPTH == 2 && 2 < NT) SLOAD(SE, 2);
;     SWRITE(1, SO); __syncthreads();
	ds_read_b128 v[0:3], v186 offset:32768
	ds_read_b128 v[4:7], v186 offset:36864
	s_waitcnt vmcnt(3) lgkmcnt(1)
	v_mfma_f32_32x32x16_bf16 v[32:47], v[0:3], v[110:113], 0
	v_or_b32_e32 v0, 32, v96
	v_bitop3_b32 v0, v0, v53, v54 bitop3:0xde
	v_add_u32_e32 v188, 0, v0
	ds_read_b128 v[0:3], v188 offset:32768
	v_and_b32_e32 v8, 0x3fffffc0, v14
	v_lshl_add_u32 v161, v8, 2, 0
	v_lshlrev_b32_e32 v8, 3, v69
	s_waitcnt lgkmcnt(1)
	v_mfma_f32_32x32x16_bf16 v[16:31], v[4:7], v[110:113], 0
	ds_read_b128 v[4:7], v188 offset:36864
	s_mov_b32 s37, s36
	s_mov_b32 s38, s36
	s_mov_b32 s39, s36
	s_mov_b32 s40, s36
	s_mov_b32 s41, s36
	s_mov_b32 s42, s36
	s_waitcnt vmcnt(2) lgkmcnt(1)
	v_mfma_f32_32x32x16_bf16 v[32:47], v[0:3], v[106:109], v[32:47]
	v_or_b32_e32 v0, 64, v96
	v_bitop3_b32 v0, v0, v53, v54 bitop3:0xde
	v_add_u32_e32 v190, 0, v0
	ds_read_b128 v[0:3], v190 offset:32768
	s_mov_b32 s43, s36
	s_mov_b32 s44, s36
	s_mov_b32 s45, s36
	s_waitcnt lgkmcnt(1)
	v_mfma_f32_32x32x16_bf16 v[16:31], v[4:7], v[106:109], v[16:31]
	v_and_b32_e32 v4, 0xc0, v52
	v_lshlrev_b32_e32 v5, 1, v14
	v_and_or_b32 v4, v8, 24, v4
	v_and_b32_e32 v5, 32, v5
	v_and_b32_e32 v6, 0x100, v8
	v_or3_b32 v70, v4, v5, v6
	ds_read_b128 v[4:7], v190 offset:36864
	s_waitcnt vmcnt(1) lgkmcnt(1)
	v_mfma_f32_32x32x16_bf16 v[32:47], v[0:3], v[102:105], v[32:47]
	v_or_b32_e32 v0, 0x60, v96
	v_bitop3_b32 v0, v0, v53, v54 bitop3:0xde
	v_add_u32_e32 v192, 0, v0
	ds_read_b128 v[0:3], v192 offset:32768
	ds_read_b128 v[52:55], v192 offset:36864
	s_mov_b32 s46, s36
	s_mov_b32 s47, s36
	s_waitcnt lgkmcnt(2)
	v_mfma_f32_32x32x16_bf16 v[16:31], v[4:7], v[102:105], v[16:31]
	s_mov_b32 s48, s36
	s_mov_b32 s49, s36
	s_mov_b32 s50, s36
	s_mov_b32 s51, s36
	v_add_u32_e32 v180, s14, v70
	v_lshl_add_u64 v[170:171], s[20:21], 0, v[48:49]
	s_mov_b32 s52, 4
	s_waitcnt vmcnt(0) lgkmcnt(1)
	v_mfma_f32_32x32x16_bf16 v[32:47], v[0:3], v[98:101], v[32:47]
	v_mov_b64_e32 v[0:1], s[36:37]
	v_mov_b64_e32 v[14:15], s[50:51]
	v_mov_b64_e32 v[2:3], s[38:39]
	v_mov_b64_e32 v[4:5], s[40:41]
	v_mov_b64_e32 v[6:7], s[42:43]
	v_mov_b64_e32 v[8:9], s[44:45]
	v_mov_b64_e32 v[10:11], s[46:47]
	s_waitcnt lgkmcnt(0)
	v_mfma_f32_32x32x16_bf16 v[16:31], v[52:55], v[98:101], v[16:31]
	s_nop 2
	v_max_f32_e32 v52, v33, v33
	v_max_f32_e32 v53, v32, v32
	v_max_f32_e32 v52, v53, v52
	v_max3_f32 v52, v52, v34, v35
	v_max3_f32 v52, v52, v36, v37
	v_max3_f32 v52, v52, v38, v39
	v_max3_f32 v52, v52, v40, v41
	v_max3_f32 v52, v52, v42, v43
	v_max3_f32 v52, v52, v44, v45
	v_max3_f32 v52, v52, v46, v47
	v_max3_f32 v52, v52, v16, v17
	v_max3_f32 v71, v52, v18, v19
	v_lshl_add_u64 v[52:53], v[164:165], 0, s[24:25]
	v_mad_u64_u32 v[54:55], s[12:13], v52, s9, v[50:51]
	v_mad_i32_i24 v55, v53, s9, v55
	v_lshl_add_u64 v[52:53], v[54:55], 0, v[48:49]
	v_lshl_add_u64 v[54:55], v[168:169], 0, s[24:25]
	v_mad_u64_u32 v[56:57], s[12:13], v54, s9, v[50:51]
	v_mad_i32_i24 v57, v55, s9, v57
	v_lshl_add_u64 v[56:57], v[56:57], 0, v[48:49]
	global_load_dwordx4 v[52:55], v[52:53], off
	s_nop 0
	global_load_dwordx4 v[56:59], v[56:57], off
	v_mov_b64_e32 v[12:13], s[48:49]
	global_load_dwordx4 v[60:63], v[60:61], off
	v_lshl_add_u32 v177, v68, 2, v161
	global_load_dwordx4 v[114:117], v[64:65], off
	v_lshl_add_u64 v[64:65], v[168:169], 0, s[88:89]
	v_mad_u64_u32 v[50:51], s[12:13], v64, s9, v[50:51]
	v_mad_i32_i24 v51, v65, s9, v51
	v_lshl_add_u64 v[50:51], v[50:51], 0, v[48:49]
	v_lshl_add_u64 v[64:65], v[166:167], 0, s[90:91]
	global_load_dwordx4 v[118:121], v[50:51], off
	global_load_dwordx4 v[122:125], v[64:65], off
	v_max3_f32 v50, v71, v20, v21
	v_max3_f32 v50, v50, v22, v23
	v_max3_f32 v50, v50, v24, v25
	v_max3_f32 v50, v50, v26, v27
	v_max3_f32 v50, v50, v28, v29
	v_max3_f32 v50, v50, v30, v31
	v_mov_b32_e32 v51, v50
	s_nop 1
	v_permlane32_swap_b32_e32 v50, v51
	v_max_f32_e32 v51, v51, v51
	v_max_f32_e32 v50, v50, v50
	v_max_f32_e32 v50, v50, v51
	v_add_f32_e32 v51, 0x7149f2ca, v50
	v_max_f32_e32 v50, 0xf149f2ca, v50
	v_cmp_ge_f32_e32 vcc, s76, v51
	v_sub_f32_e32 v51, 0xf149f2ca, v50
	v_mul_f32_e32 v51, 0x3e38aa3b, v51
	v_exp_f32_e32 v51, v51
	s_cmp_eq_u64 vcc, exec
	s_cselect_b64 vcc, -1, 0
	v_cndmask_b32_e32 v142, v50, v193, vcc
	v_mul_f32_e32 v50, 0xbe38aa3b, v142
	v_cndmask_b32_e64 v194, v51, 1.0, vcc
	v_mov_b32_e32 v51, v50
	v_fmamk_f32 v32, v32, 0x3e38aa3b, v50
	v_fmamk_f32 v33, v33, 0x3e38aa3b, v50
	v_fmamk_f32 v34, v34, 0x3e38aa3b, v50
	v_fmamk_f32 v35, v35, 0x3e38aa3b, v50
	v_fmamk_f32 v36, v36, 0x3e38aa3b, v50
	v_fmamk_f32 v37, v37, 0x3e38aa3b, v50
	v_fmamk_f32 v38, v38, 0x3e38aa3b, v50
	v_fmamk_f32 v39, v39, 0x3e38aa3b, v50
	v_fmamk_f32 v40, v40, 0x3e38aa3b, v50
	v_fmamk_f32 v41, v41, 0x3e38aa3b, v50
	v_fmamk_f32 v42, v42, 0x3e38aa3b, v50
	v_fmamk_f32 v43, v43, 0x3e38aa3b, v50
	v_fmamk_f32 v44, v44, 0x3e38aa3b, v50
	v_fmamk_f32 v45, v45, 0x3e38aa3b, v50
	v_fmamk_f32 v46, v46, 0x3e38aa3b, v50
	v_fmac_f32_e32 v51, 0x3e38aa3b, v47
	v_exp_f32_e32 v217, v32
	v_exp_f32_e32 v219, v33
	v_exp_f32_e32 v208, v34
	v_exp_f32_e32 v218, v35
	v_exp_f32_e32 v153, v36
	v_exp_f32_e32 v216, v37
	v_exp_f32_e32 v152, v38
	v_exp_f32_e32 v202, v39
	v_exp_f32_e32 v149, v40
	v_exp_f32_e32 v151, v41
	v_exp_f32_e32 v147, v42
	v_exp_f32_e32 v150, v43
	v_exp_f32_e32 v145, v44
	v_exp_f32_e32 v148, v45
	v_exp_f32_e32 v144, v46
	v_exp_f32_e32 v146, v51
	v_pk_fma_f32 v[132:133], v[30:31], s[8:9], v[50:51] op_sel_hi:[1,0,0]
	v_pk_fma_f32 v[134:135], v[28:29], s[8:9], v[50:51] op_sel_hi:[1,0,0]
	v_pk_fma_f32 v[140:141], v[26:27], s[8:9], v[50:51] op_sel_hi:[1,0,0]
	v_pk_fma_f32 v[126:127], v[24:25], s[8:9], v[50:51] op_sel_hi:[1,0,0]
	v_pk_fma_f32 v[128:129], v[22:23], s[8:9], v[50:51] op_sel_hi:[1,0,0]
	v_pk_fma_f32 v[130:131], v[20:21], s[8:9], v[50:51] op_sel_hi:[1,0,0]
	v_pk_fma_f32 v[136:137], v[18:19], s[8:9], v[50:51] op_sel_hi:[1,0,0]
	v_pk_fma_f32 v[138:139], v[16:17], s[8:9], v[50:51] op_sel_hi:[1,0,0]
	s_waitcnt vmcnt(5)
	ds_write_b128 v181, v[52:55] offset:16384
	s_waitcnt vmcnt(4)
	ds_write_b128 v184, v[56:59] offset:16384
	s_waitcnt vmcnt(3)
	ds_write_b128 v182, v[60:63] offset:40960
	s_addk_i32 s14, 0x4000
	v_mov_b64_e32 v[30:31], v[14:15]
	v_mov_b64_e32 v[46:47], v[14:15]
	v_mov_b64_e32 v[62:63], v[14:15]
	v_cmp_gt_u32_e64 s[12:13], 32, v69
	v_add_u32_e32 v179, s14, v70
	v_mov_b32_e32 v178, 0
	v_mov_b64_e32 v[28:29], v[12:13]
	v_mov_b64_e32 v[26:27], v[10:11]
	v_mov_b64_e32 v[24:25], v[8:9]
	v_mov_b64_e32 v[22:23], v[6:7]
	v_mov_b64_e32 v[20:21], v[4:5]
	v_mov_b64_e32 v[18:19], v[2:3]
	v_mov_b64_e32 v[16:17], v[0:1]
	v_mov_b64_e32 v[44:45], v[12:13]
	v_mov_b64_e32 v[42:43], v[10:11]
	v_mov_b64_e32 v[40:41], v[8:9]
	v_mov_b64_e32 v[38:39], v[6:7]
	v_mov_b64_e32 v[36:37], v[4:5]
	v_mov_b64_e32 v[34:35], v[2:3]
	v_mov_b64_e32 v[32:33], v[0:1]
	v_mov_b64_e32 v[60:61], v[12:13]
	v_mov_b64_e32 v[58:59], v[10:11]
	v_mov_b64_e32 v[56:57], v[8:9]
	v_mov_b64_e32 v[54:55], v[6:7]
	v_mov_b64_e32 v[52:53], v[4:5]
	v_mov_b64_e32 v[50:51], v[2:3]
	v_mov_b64_e32 v[48:49], v[0:1]
	s_waitcnt lgkmcnt(0)
	s_barrier

; __device__ __forceinline__ int v_st(int k, int c) { const int kk = (k & ~0xC) | ((k & 4) << 1) | ((k & 8) >> 1); return ((kk >> 3) * 4 + (c >> 5)) * 512 + ((kk & 7) * 32 + (c & 31)) * 2; }
; __device__ __forceinline__ int v_rd_base(int lane) { return ((lane & 3) << 3) | (((lane >> 2) & 3) << 6) | (((lane >> 4) & 1) << 5) | (((lane >> 5) & 1) << 8); }
; template <int DQK, int DK1, int LDQ, int LDK, int LDKR, int LDV, int NQL, int SDEPTH>
; __device__ __forceinline__ void attn_core(const AttnArgs& a, char* lds, f32x16 (&o)[4]) {
;     ...
;     char* QL = lds + 2 * SHM_V + 2 * SHM_K + 2048 + tid * 16;
;     { const bf16_t* Qw = a.Q + (long)(wid * 32 + r32) * LDQ + hi * 8;
; #pragma unroll
;       for (int d0 = 0; d0 < NQR; ++d0) qr[d0] = *(const bf16x8*)(Qw + d0 * 16);
; #pragma unroll
;       for (int d0 = NQR; d0 < ND0; ++d0) *(bf16x8*)(QL + (d0 - NQR) * 8192) = *(const bf16x8*)(Qw + d0 * 16); }
;     const int sr = tid >> 4, sc = (tid & 15) * 8, vst0 = v_st(sr, sc), vst1 = v_st(32 + sr, sc);
;     const int vb0 = (int)(uintptr_t)V_lds + v_rd_base(lane);
;     const bf16_t* kptr[KCH]; int kld[KCH], kwo[KCH];
; #pragma unroll
;     for (int c = 0; c < KCH; ++c) { const int idx = tid + c * 512, kr_ = idx / CPR, kc = (idx % CPR) * 8;
;         if (kc < DK1) { kptr[c] = a.Kn + (long)kr_ * LDK + kc; kld[c] = LDK; } else { kptr[c] = a.Kr + (long)kr_ * LDKR + (kc - DK1); kld[c] = LDKR; }
;         kwo[c] = kr_ * KP + ((kc * 2) ^ ((kr_ & 7) << 4)); }
;     struct { bf16x8 vs0, vs1, ks[KCH]; } sr_[SDEPTH];
;     int kb[4];
; #pragma unroll
;     for (int m = 0; m < 4; ++m) kb[m] = r32 * KP + ((m * 32 + hi * 16) ^ ((r32 & 7) << 4));
.LBB0_206:
	s_and_b32 s24, s14, 7
	s_mul_i32 s15, s23, 0xc00
	s_mul_hi_i32 s14, s23, 0xc00
	s_add_u32 s15, s4, s15
	s_addc_u32 s14, s5, s14
	s_mul_i32 s20, s24, 0x180
	s_add_u32 s20, s15, s20
	v_mov_b32_e32 v9, v159
	s_addc_u32 s21, s14, 0
	s_lshl_b32 s14, s24, 9
	v_ashrrev_i32_e32 v0, 1, v9
	v_bfe_u32 v2, v9, 5, 1
	v_bfi_b32 v3, s33, v0, v9
	v_mov_b64_e32 v[0:1], s[20:21]
	v_lshlrev_b32_e32 v8, 4, v9
	v_mad_i64_i32 v[0:1], s[20:21], v3, s77, v[0:1]
	v_lshlrev_b32_e32 v96, 4, v2
	v_lshl_add_u64 v[4:5], v[0:1], 0, v[96:97]
	v_add_u32_e32 v0, 0, v8
	global_load_dwordx4 v[126:129], v[4:5], off
	global_load_dwordx4 v[122:125], v[4:5], off offset:32
	global_load_dwordx4 v[118:121], v[4:5], off offset:64
	global_load_dwordx4 v[114:117], v[4:5], off offset:96
	global_load_dwordx4 v[110:113], v[4:5], off offset:128
	global_load_dwordx4 v[106:109], v[4:5], off offset:160
	global_load_dwordx4 v[102:105], v[4:5], off offset:192
	global_load_dwordx4 v[98:101], v[4:5], off offset:224
	v_add_u32_e32 v181, 0x14800, v0
	global_load_dwordx4 v[64:67], v[4:5], off offset:256
	global_load_dwordx4 v[68:71], v[4:5], off offset:288
	global_load_dwordx4 v[72:75], v[4:5], off offset:320
	global_load_dwordx4 v[76:79], v[4:5], off offset:352
	s_add_u32 s14, s6, s14
	s_addc_u32 s15, s7, 0
	v_mul_hi_i32 v0, v9, s86
	v_lshrrev_b32_e32 v1, 31, v0
	v_ashrrev_i32_e32 v0, 2, v0
	v_add_u32_e32 v0, v0, v1
	v_mul_lo_u32 v1, v0, 24
	v_sub_u32_e32 v10, v9, v1
	v_lshlrev_b32_e32 v2, 3, v10
	v_cmp_lt_i32_e32 vcc, 15, v10
	v_ashrrev_i32_e32 v1, 31, v0
	s_and_saveexec_b64 s[20:21], vcc
	s_xor_b64 s[20:21], exec, s[20:21]
	v_lshlrev_b64 v[4:5], 7, v[0:1]
	v_lshl_add_u64 v[4:5], s[18:19], 0, v[4:5]
	v_mov_b32_e32 v3, v97
	s_movk_i32 s38, 0xff00
	v_lshl_add_u64 v[2:3], v[2:3], 1, v[4:5]
	s_mov_b32 s39, -1
	v_lshl_add_u64 v[162:163], v[2:3], 0, s[38:39]
	s_or_saveexec_b64 s[20:21], s[20:21]
	v_mov_b64_e32 v[164:165], 64
	s_xor_b64 exec, exec, s[20:21]
	v_lshlrev_b64 v[4:5], 12, v[0:1]
	v_lshl_add_u64 v[4:5], s[14:15], 0, v[4:5]
	v_ashrrev_i32_e32 v3, 31, v2
	v_lshl_add_u64 v[162:163], v[2:3], 1, v[4:5]
	v_mov_b64_e32 v[164:165], 0x800
	s_or_b64 exec, exec, s[20:21]
	v_add_u32_e32 v1, 0x200, v9
	v_mul_hi_i32 v2, v1, s86
	v_lshrrev_b32_e32 v3, 31, v2
	v_ashrrev_i32_e32 v2, 2, v2
	v_add_u32_e32 v4, v2, v3
	v_mul_lo_u32 v2, v4, 24
	v_sub_u32_e32 v11, v1, v2
	v_lshlrev_b32_e32 v2, 3, v11
	v_cmp_lt_i32_e32 vcc, 15, v11
	v_ashrrev_i32_e32 v5, 31, v4
	s_and_saveexec_b64 s[20:21], vcc
	s_xor_b64 s[20:21], exec, s[20:21]
	v_lshlrev_b64 v[6:7], 7, v[4:5]
	v_lshl_add_u64 v[6:7], s[18:19], 0, v[6:7]
	v_mov_b32_e32 v3, v97
	s_movk_i32 s38, 0xff00
	v_lshl_add_u64 v[2:3], v[2:3], 1, v[6:7]
	s_mov_b32 s39, -1
	v_lshl_add_u64 v[166:167], v[2:3], 0, s[38:39]
	s_or_saveexec_b64 s[20:21], s[20:21]
	v_mov_b64_e32 v[168:169], 64
	s_xor_b64 exec, exec, s[20:21]
	v_lshlrev_b64 v[6:7], 12, v[4:5]
	v_lshl_add_u64 v[6:7], s[14:15], 0, v[6:7]
	v_ashrrev_i32_e32 v3, 31, v2
	v_lshl_add_u64 v[166:167], v[2:3], 1, v[6:7]
	v_mov_b64_e32 v[168:169], 0x800
	s_or_b64 exec, exec, s[20:21]
	v_add_u32_e32 v1, 0x400, v9
	v_mul_hi_i32 v2, v1, s86
	v_lshrrev_b32_e32 v3, 31, v2
	v_ashrrev_i32_e32 v2, 2, v2
	v_add_u32_e32 v2, v2, v3
	v_mul_lo_u32 v3, v2, 24
	v_sub_u32_e32 v1, v1, v3
	v_lshlrev_b32_e32 v6, 3, v1
	v_cmp_lt_i32_e32 vcc, 15, v1
	v_ashrrev_i32_e32 v3, 31, v2
	s_and_saveexec_b64 s[20:21], vcc
	s_xor_b64 s[20:21], exec, s[20:21]
	v_lshlrev_b64 v[12:13], 7, v[2:3]
	v_lshl_add_u64 v[12:13], s[18:19], 0, v[12:13]
	v_mov_b32_e32 v7, v97
	s_movk_i32 s38, 0xff00
	v_lshl_add_u64 v[6:7], v[6:7], 1, v[12:13]
	s_mov_b32 s39, -1
	v_lshl_add_u64 v[170:171], v[6:7], 0, s[38:39]
	s_or_saveexec_b64 s[20:21], s[20:21]
	v_mov_b64_e32 v[172:173], 64
	s_xor_b64 exec, exec, s[20:21]
	v_lshlrev_b64 v[12:13], 12, v[2:3]
	v_lshl_add_u64 v[12:13], s[14:15], 0, v[12:13]
	v_ashrrev_i32_e32 v7, 31, v6
	v_lshl_add_u64 v[170:171], v[6:7], 1, v[12:13]
	v_mov_b64_e32 v[172:173], 0x800
	s_or_b64 exec, exec, s[20:21]
	v_mul_lo_u32 v3, v4, s84
	v_lshrrev_b32_e32 v248, 1, v4
	v_bitop3_b32 v4, v248, v11, 7 bitop3:0x6c
	v_ashrrev_i32_e32 v174, 4, v9
	v_lshl_add_u32 v20, v4, 4, v3
	v_and_b32_e32 v4, 0xfffff0, v174
	v_lshlrev_b32_e32 v5, 1, v174
	v_and_or_b32 v4, v5, 8, v4
	v_lshrrev_b32_e32 v5, 1, v174
	v_and_b32_e32 v6, 3, v174
	v_mul_lo_u32 v3, v0, s84
	v_lshrrev_b32_e32 v249, 1, v0
	v_bitop3_b32 v0, v249, v10, 7 bitop3:0x6c
	v_and_or_b32 v5, v5, 4, v6
	v_add_u32_e32 v6, 32, v174
	v_lshl_add_u32 v21, v0, 4, v3
	v_and_b32_e32 v0, 0x3fffffc0, v9
	s_add_i32 s20, 0, 0x14000
	v_and_b32_e32 v7, 0xfffff0, v6
	v_lshlrev_b32_e32 v6, 1, v6
	v_and_b32_e32 v52, 63, v9
	v_lshl_add_u32 v161, v0, 2, s20
	v_lshlrev_b32_e32 v0, 3, v9
	v_and_or_b32 v6, v6, 8, v7
	v_and_b32_e32 v3, 0x78, v0
	v_lshrrev_b32_e32 v4, 1, v4
	v_bfe_u32 v0, v0, 5, 2
	v_lshrrev_b32_e32 v6, 1, v6
	v_lshlrev_b32_e32 v7, 4, v52
	v_and_b32_e32 v51, 31, v9
	v_or_b32_e32 v4, v4, v0
	v_or_b32_e32 v0, v6, v0
	v_lshlrev_b32_e32 v6, 3, v52
	v_and_b32_e32 v7, 0xc0, v7
	v_lshlrev_b32_e32 v9, 1, v52
	v_and_or_b32 v7, v6, 24, v7
	v_and_b32_e32 v9, 32, v9
	v_and_b32_e32 v6, 0x100, v6
	v_or3_b32 v53, v7, v9, v6
	v_mul_lo_u32 v6, v2, s84
	v_lshrrev_b32_e32 v250, 1, v2
	v_bitop3_b32 v1, v250, v1, 7 bitop3:0x6c
	s_lshl_b32 s20, s68, 6
	v_lshlrev_b32_e32 v5, 6, v5
	v_lshlrev_b32_e32 v0, 9, v0
	v_lshl_add_u32 v22, v1, 4, v6
	v_and_b32_e32 v1, 48, v8
	s_sub_i32 s20, s28, s20
	v_or3_b32 v23, v0, v5, v1
	v_mul_u32_u24_e32 v0, 0x180, v51
	v_lshlrev_b32_e32 v2, 3, v51
	v_and_b32_e32 v2, 0x70, v2
	v_or_b32_e32 v6, 32, v96
	s_and_b64 s[12:13], s[12:13], exec
	v_bitop3_b32 v50, v6, v0, v2 bitop3:0xde
	v_or_b32_e32 v6, 64, v96
; #define SLOAD(i, j) do { const long rb_ = KROW(j); sr_[i].vs0 = *(const bf16x8*)(a.V + (rb_ + sr) * LDV + sc); sr_[i].vs1 = *(const bf16x8*)(a.V + (rb_ + 32 + sr) * LDV + sc); \
;     _Pragma("unroll") for (int c_ = 0; c_ < KCH; ++c_) sr_[i].ks[c_] = *(const bf16x8*)(kptr[c_] + rb_ * kld[c_]); } while (0)
; #define SWRITE(b, i) do { *(bf16x8*)(V_lds + (b) * SHM_V + vst0) = sr_[i].vs0; *(bf16x8*)(V_lds + (b) * SHM_V + vst1) = sr_[i].vs1; \
;     _Pragma("unroll") for (int c_ = 0; c_ < KCH; ++c_) *(bf16x8*)(K_lds + (b) * SHM_K + kwo[c_]) = sr_[i].ks[c_]; } while (0)
; template <int DQK, int DK1, int LDQ, int LDK, int LDKR, int LDV, int NQL, int SDEPTH>
; __device__ __forceinline__ void attn_core(const AttnArgs& a, char* lds, f32x16 (&o)[4]) {
;     ...
;     f32x16 pA0, pA1, pB0, pB1; float mnA, mnB, alA, alB; bf16x8 pa0, pa1, pa2, pa3; const int NT = a.NT;
;     constexpr int SE = 0, SO = SDEPTH - 1;
;     SLOAD(SE, 0); asm volatile("s_waitcnt vmcnt(0)" ::: "memory"); SWRITE(0, SE); __syncthreads();
;     QKT(pA0, pA1, K_lds); partialSM(pA0, pA1, m_reg, mnA, alA, a.C, a.thr);
	s_cselect_b32 s12, s25, s20
	v_ashrrev_i32_e32 v175, 31, v174
	v_lshlrev_b32_e32 v4, 9, v4
	v_bitop3_b32 v62, v6, v0, v2 bitop3:0xde
	v_or_b32_e32 v6, 0x60, v96
	s_ashr_i32 s13, s12, 31
	v_lshl_add_u64 v[176:177], v[174:175], 0, 32
	v_bitop3_b32 v24, v96, v0, v2 bitop3:0xde
	v_bitop3_b32 v63, v6, v0, v2 bitop3:0xde
	v_or3_b32 v25, v4, v5, v1
	v_lshl_add_u64 v[0:1], v[174:175], 0, s[12:13]
	v_lshl_add_u64 v[4:5], v[176:177], 0, s[12:13]
	v_lshlrev_b64 v[0:1], 12, v[0:1]
	v_lshlrev_b64 v[4:5], 12, v[4:5]
	v_lshl_add_u64 v[0:1], s[14:15], 0, v[0:1]
	v_lshlrev_b32_e32 v48, 1, v3
	v_mov_b32_e32 v49, v97
	v_lshl_add_u64 v[4:5], s[14:15], 0, v[4:5]
	v_mad_i64_i32 v[8:9], s[20:21], v164, s12, 0
	v_mad_i64_i32 v[12:13], s[20:21], v168, s12, 0
	v_mad_i64_i32 v[16:17], s[20:21], v172, s12, 0
	v_lshl_add_u64 v[0:1], v[0:1], 0, v[48:49]
	v_lshl_add_u64 v[4:5], v[4:5], 0, v[48:49]
	v_lshl_add_u64 v[8:9], v[8:9], 1, v[162:163]
	v_lshl_add_u64 v[12:13], v[12:13], 1, v[166:167]
	v_lshl_add_u64 v[16:17], v[16:17], 1, v[170:171]
	global_load_dwordx4 v[0:3], v[0:1], off offset:256
	v_add_u32_e32 v186, 0, v25
	global_load_dwordx4 v[4:7], v[4:5], off offset:256
	v_add_u32_e32 v188, 0, v23
	global_load_dwordx4 v[8:11], v[8:9], off
	v_add_u32_e32 v194, 0, v21
	global_load_dwordx4 v[12:15], v[12:13], off
	v_add_u32_e32 v196, 0, v20
	global_load_dwordx4 v[16:19], v[16:17], off
	v_add_u32_e32 v198, 0, v22
	v_add_u32_e32 v184, 0, v24
	s_waitcnt vmcnt(0)
	v_add_u32_e32 v192, 0, v50
	v_add_u32_e32 v190, 0, v62
	v_add_u32_e32 v173, 0, v63
	s_mov_b32 s37, s36
	s_mov_b32 s38, s36
	s_mov_b32 s39, s36
	s_mov_b32 s40, s36
	s_mov_b32 s41, s36
	s_mov_b32 s42, s36
	s_mov_b32 s43, s36
	s_mov_b32 s44, s36
	s_mov_b32 s45, s36
	s_mov_b32 s46, s36
	s_mov_b32 s47, s36
	s_mov_b32 s48, s36
	s_mov_b32 s49, s36
	s_mov_b32 s50, s36
	s_mov_b32 s51, s36
	v_lshl_add_u32 v165, v51, 2, v161
	v_lshl_add_u64 v[178:179], s[14:15], 0, v[48:49]
	s_mov_b32 s69, 2
	v_add_u32_e32 v216, 0xe000, v184
	v_add_u32_e32 v208, 0xe000, v192
	v_add_u32_e32 v206, 0xe000, v190
	v_add_u32_e32 v202, 0xe000, v173
	v_mov_b32_e32 v182, 0
	s_waitcnt vmcnt(0)
	ds_write_b128 v181, v[64:67]
	ds_write_b128 v181, v[68:71] offset:8192
	ds_write_b128 v181, v[72:75] offset:16384
	ds_write_b128 v181, v[76:79] offset:24576
	ds_write_b128 v186, v[0:3]
	ds_write_b128 v188, v[4:7]
	ds_write_b128 v194, v[8:11] offset:32768
	ds_write_b128 v196, v[12:15] offset:32768
	v_mov_b64_e32 v[0:1], s[36:37]
	ds_write_b128 v198, v[16:19] offset:32768
	s_waitcnt lgkmcnt(0)
	s_barrier
	ds_read_b128 v[16:19], v184 offset:32768
	ds_read_b128 v[20:23], v184 offset:45056
	s_waitcnt lgkmcnt(1)
	v_mfma_f32_32x32x16_bf16 v[32:47], v[16:19], v[126:129], 0
	ds_read_b128 v[54:57], v192 offset:32768
	ds_read_b128 v[58:61], v192 offset:45056
	v_mov_b64_e32 v[14:15], s[50:51]
	v_mov_b64_e32 v[2:3], s[38:39]
	v_mov_b64_e32 v[4:5], s[40:41]
	v_mov_b64_e32 v[6:7], s[42:43]
	v_mov_b64_e32 v[8:9], s[44:45]
	v_mov_b64_e32 v[10:11], s[46:47]
	s_waitcnt lgkmcnt(2)
	v_mfma_f32_32x32x16_bf16 v[16:31], v[20:23], v[126:129], 0
	v_mov_b64_e32 v[12:13], s[48:49]
	s_movk_i32 s37, 0x80
	s_waitcnt lgkmcnt(1)
	v_mfma_f32_32x32x16_bf16 v[32:47], v[54:57], v[122:125], v[32:47]
	s_waitcnt lgkmcnt(0)
	v_mfma_f32_32x32x16_bf16 v[16:31], v[58:61], v[122:125], v[16:31]
	ds_read_b128 v[54:57], v190 offset:32768
	ds_read_b128 v[58:61], v190 offset:45056
	s_waitcnt lgkmcnt(1)
	v_mfma_f32_32x32x16_bf16 v[32:47], v[54:57], v[118:121], v[32:47]
	s_waitcnt lgkmcnt(0)
	v_mfma_f32_32x32x16_bf16 v[16:31], v[58:61], v[118:121], v[16:31]
	ds_read_b128 v[54:57], v173 offset:32768
	ds_read_b128 v[58:61], v173 offset:45056
	s_waitcnt lgkmcnt(1)
	v_mfma_f32_32x32x16_bf16 v[32:47], v[54:57], v[114:117], v[32:47]
	s_waitcnt lgkmcnt(0)
	v_mfma_f32_32x32x16_bf16 v[16:31], v[58:61], v[114:117], v[16:31]
	ds_read_b128 v[54:57], v184 offset:32896
	ds_read_b128 v[58:61], v184 offset:45184
	s_waitcnt lgkmcnt(1)
	v_mfma_f32_32x32x16_bf16 v[32:47], v[54:57], v[110:113], v[32:47]
	s_waitcnt lgkmcnt(0)
	v_mfma_f32_32x32x16_bf16 v[16:31], v[58:61], v[110:113], v[16:31]
	ds_read_b128 v[54:57], v192 offset:32896
	ds_read_b128 v[58:61], v192 offset:45184
	s_waitcnt lgkmcnt(1)
	v_mfma_f32_32x32x16_bf16 v[32:47], v[54:57], v[106:109], v[32:47]
	s_waitcnt lgkmcnt(0)
	v_mfma_f32_32x32x16_bf16 v[16:31], v[58:61], v[106:109], v[16:31]
	ds_read_b128 v[54:57], v190 offset:32896
	ds_read_b128 v[58:61], v190 offset:45184
	s_waitcnt lgkmcnt(1)
	v_mfma_f32_32x32x16_bf16 v[32:47], v[54:57], v[102:105], v[32:47]
	s_waitcnt lgkmcnt(0)
	v_mfma_f32_32x32x16_bf16 v[16:31], v[58:61], v[102:105], v[16:31]
	ds_read_b128 v[54:57], v173 offset:32896
	ds_read_b128 v[58:61], v173 offset:45184
	s_waitcnt lgkmcnt(1)
	v_mfma_f32_32x32x16_bf16 v[32:47], v[54:57], v[98:101], v[32:47]
	s_waitcnt lgkmcnt(0)
	v_mfma_f32_32x32x16_bf16 v[16:31], v[58:61], v[98:101], v[16:31]
	ds_read_b128 v[54:57], v184 offset:33024
	ds_read_b128 v[58:61], v184 offset:45312
	ds_read_b128 v[62:65], v181
	s_waitcnt lgkmcnt(0)
	v_mfma_f32_32x32x16_bf16 v[32:47], v[54:57], v[62:65], v[32:47]
	v_mfma_f32_32x32x16_bf16 v[16:31], v[58:61], v[62:65], v[16:31]
	ds_read_b128 v[54:57], v192 offset:33024
	ds_read_b128 v[58:61], v192 offset:45312
	ds_read_b128 v[62:65], v181 offset:8192
	s_waitcnt lgkmcnt(0)
	v_mfma_f32_32x32x16_bf16 v[32:47], v[54:57], v[62:65], v[32:47]
	v_mfma_f32_32x32x16_bf16 v[16:31], v[58:61], v[62:65], v[16:31]
	ds_read_b128 v[54:57], v190 offset:33024
	ds_read_b128 v[58:61], v190 offset:45312
	ds_read_b128 v[62:65], v181 offset:16384
	s_waitcnt lgkmcnt(0)
; #define SLOAD(i, j) do { const long rb_ = KROW(j); sr_[i].vs0 = *(const bf16x8*)(a.V + (rb_ + sr) * LDV + sc); sr_[i].vs1 = *(const bf16x8*)(a.V + (rb_ + 32 + sr) * LDV + sc); \
;     _Pragma("unroll") for (int c_ = 0; c_ < KCH; ++c_) sr_[i].ks[c_] = *(const bf16x8*)(kptr[c_] + rb_ * kld[c_]); } while (0)
; #define SWRITE(b, i) do { *(bf16x8*)(V_lds + (b) * SHM_V + vst0) = sr_[i].vs0; *(bf16x8*)(V_lds + (b) * SHM_V + vst1) = sr_[i].vs1; \
;     _Pragma("unroll") for (int c_ = 0; c_ < KCH; ++c_) *(bf16x8*)(K_lds + (b) * SHM_K + kwo[c_]) = sr_[i].ks[c_]; } while (0)
; __device__ __forceinline__ void partialSM(f32x16& p0, f32x16& p1, float& m_reg, float& mn, float& alpha, const float C, const float thr) {
;     float pmax = p0[0];
; #pragma unroll
;     for (int r = 1; r < 16; ++r) pmax = fmaxf(pmax, p0[r]);
; #pragma unroll
;     for (int r = 0; r < 16; ++r) pmax = fmaxf(pmax, p1[r]);
;     { auto rr = __builtin_amdgcn_permlane32_swap(__float_as_uint(pmax), __float_as_uint(pmax), false, false);
;       pmax = fmaxf(__uint_as_float(rr[0]), __uint_as_float(rr[1])); }
;     if (__builtin_expect(__all(pmax - m_reg <= thr), 1)) { mn = m_reg; alpha = 1.f; }
;     else { mn = fmaxf(m_reg, pmax); alpha = __builtin_amdgcn_exp2f((m_reg - mn) * C); m_reg = mn; }
;     const float mnC = -mn * C;
; #pragma unroll
;     for (int r = 0; r < 16; ++r) p0[r] = fmaf(p0[r], C, mnC);
; #pragma unroll
;     for (int r = 0; r < 16; ++r) p1[r] = fmaf(p1[r], C, mnC);
; #pragma unroll
;     for (int r = 0; r < 16; ++r) p0[r] = __builtin_amdgcn_exp2f(p0[r]);
; }
; template <int DQK, int DK1, int LDQ, int LDK, int LDKR, int LDV, int NQL, int SDEPTH>
; __device__ __forceinline__ void attn_core(const AttnArgs& a, char* lds, f32x16 (&o)[4]) {
;     ...
;     SLOAD(SE, 0); asm volatile("s_waitcnt vmcnt(0)" ::: "memory"); SWRITE(0, SE); __syncthreads();
;     QKT(pA0, pA1, K_lds); partialSM(pA0, pA1, m_reg, mnA, alA, a.C, a.thr);
;     SLOAD(SO, 1); if (SDEPTH == 2 && 2 < NT) SLOAD(SE, 2);
;     SWRITE(1, SO); __syncthreads();
	v_mfma_f32_32x32x16_bf16 v[32:47], v[54:57], v[62:65], v[32:47]
	v_mfma_f32_32x32x16_bf16 v[16:31], v[58:61], v[62:65], v[16:31]
	ds_read_b128 v[54:57], v173 offset:33024
	ds_read_b128 v[58:61], v173 offset:45312
	ds_read_b128 v[62:65], v181 offset:24576
	s_waitcnt lgkmcnt(0)
	v_mfma_f32_32x32x16_bf16 v[32:47], v[54:57], v[62:65], v[32:47]
	v_mfma_f32_32x32x16_bf16 v[16:31], v[58:61], v[62:65], v[16:31]
	s_nop 10
	v_max_f32_e32 v50, v33, v33
	v_max_f32_e32 v54, v32, v32
	v_max_f32_e32 v50, v54, v50
	v_max3_f32 v50, v50, v34, v35
	v_max3_f32 v50, v50, v36, v37
	v_max3_f32 v50, v50, v38, v39
	v_max3_f32 v50, v50, v40, v41
	v_max3_f32 v50, v50, v42, v43
	v_max3_f32 v50, v50, v44, v45
	v_max3_f32 v50, v50, v46, v47
	v_max3_f32 v50, v50, v16, v17
	v_max3_f32 v50, v50, v18, v19
	v_max3_f32 v50, v50, v20, v21
	v_max3_f32 v50, v50, v22, v23
	v_max3_f32 v50, v50, v24, v25
	v_max3_f32 v50, v50, v26, v27
	v_max3_f32 v50, v50, v28, v29
	v_max3_f32 v50, v50, v30, v31
	v_mov_b32_e32 v54, v50
	s_nop 1
	v_permlane32_swap_b32_e32 v50, v54
	v_max_f32_e32 v54, v54, v54
	v_max_f32_e32 v50, v50, v50
	v_max_f32_e32 v50, v50, v54
	v_add_f32_e32 v54, 0x7149f2ca, v50
	v_cmp_ge_f32_e32 vcc, s72, v54
	s_cmp_eq_u64 vcc, exec
	s_cselect_b64 vcc, -1, 0
	v_max_f32_e32 v50, 0xf149f2ca, v50
	v_cndmask_b32_e32 v204, v50, v193, vcc
	v_sub_f32_e32 v54, 0xf149f2ca, v50
	v_mul_f32_e32 v50, 0xbdd53b94, v204
	s_or_b32 s12, s12, 64
	v_fmamk_f32 v32, v32, 0x3dd53b94, v50
	v_fmamk_f32 v33, v33, 0x3dd53b94, v50
	s_ashr_i32 s13, s12, 31
	v_fmamk_f32 v36, v36, 0x3dd53b94, v50
	v_fmamk_f32 v37, v37, 0x3dd53b94, v50
	v_exp_f32_e32 v219, v32
	v_exp_f32_e32 v221, v33
	v_lshl_add_u64 v[32:33], v[174:175], 0, s[12:13]
	v_exp_f32_e32 v156, v36
	v_exp_f32_e32 v218, v37
	v_lshlrev_b64 v[32:33], 12, v[32:33]
	v_lshl_add_u64 v[36:37], v[176:177], 0, s[12:13]
	v_lshl_add_u64 v[32:33], s[14:15], 0, v[32:33]
	v_lshlrev_b64 v[36:37], 12, v[36:37]
	v_fmamk_f32 v34, v34, 0x3dd53b94, v50
	v_fmamk_f32 v35, v35, 0x3dd53b94, v50
	v_fmamk_f32 v40, v40, 0x3dd53b94, v50
	v_fmamk_f32 v41, v41, 0x3dd53b94, v50
	v_lshl_add_u64 v[32:33], v[32:33], 0, v[48:49]
	v_lshl_add_u64 v[36:37], s[14:15], 0, v[36:37]
	v_fmamk_f32 v38, v38, 0x3dd53b94, v50
	v_fmamk_f32 v39, v39, 0x3dd53b94, v50
	v_fmamk_f32 v44, v44, 0x3dd53b94, v50
	v_fmamk_f32 v45, v45, 0x3dd53b94, v50
	v_exp_f32_e32 v157, v34
	v_exp_f32_e32 v220, v35
	v_exp_f32_e32 v151, v40
	v_exp_f32_e32 v153, v41
	global_load_dwordx4 v[32:35], v[32:33], off offset:256
	v_lshl_add_u64 v[36:37], v[36:37], 0, v[48:49]
	v_mad_i64_i32 v[40:41], s[20:21], v164, s12, 0
	v_fmamk_f32 v42, v42, 0x3dd53b94, v50
	v_fmamk_f32 v43, v43, 0x3dd53b94, v50
	v_exp_f32_e32 v154, v38
	v_exp_f32_e32 v155, v39
	v_exp_f32_e32 v147, v44
	v_exp_f32_e32 v149, v45
	global_load_dwordx4 v[36:39], v[36:37], off offset:256
	v_lshl_add_u64 v[40:41], v[40:41], 1, v[162:163]
	v_mad_i64_i32 v[44:45], s[20:21], v168, s12, 0
	v_mul_f32_e32 v58, 0x3dd53b94, v54
	v_fmamk_f32 v46, v46, 0x3dd53b94, v50
	v_fmamk_f32 v47, v47, 0x3dd53b94, v50
	v_exp_f32_e32 v150, v42
	v_exp_f32_e32 v152, v43
	global_load_dwordx4 v[40:43], v[40:41], off
	v_lshl_add_u64 v[44:45], v[44:45], 1, v[166:167]
	v_mad_i64_i32 v[54:55], s[12:13], v172, s12, 0
	v_exp_f32_e32 v146, v46
	v_exp_f32_e32 v148, v47
	global_load_dwordx4 v[44:47], v[44:45], off
	v_lshl_add_u64 v[54:55], v[54:55], 1, v[170:171]
	global_load_dwordx4 v[54:57], v[54:55], off
	v_exp_f32_e32 v58, v58
	s_cmp_lg_u32 0, -1
	s_cselect_b32 s20, 0, 0
	v_add_u32_e32 v200, s20, v53
	s_addk_i32 s20, 0x4000
	s_waitcnt vmcnt(4)
	ds_write_b128 v186, v[32:35] offset:16384
	s_waitcnt vmcnt(3)
	ds_write_b128 v188, v[36:39] offset:16384
	s_waitcnt vmcnt(2)
	ds_write_b128 v194, v[40:43] offset:57344
	s_waitcnt vmcnt(1)
	ds_write_b128 v196, v[44:47] offset:57344
	s_waitcnt vmcnt(0)
	ds_write_b128 v198, v[54:57] offset:57344
	v_cndmask_b32_e64 v217, v58, 1.0, vcc
	v_pk_fma_f32 v[136:137], v[30:31], s[60:61], v[50:51] op_sel_hi:[1,0,0]
	v_pk_fma_f32 v[138:139], v[28:29], s[60:61], v[50:51] op_sel_hi:[1,0,0]
	v_pk_fma_f32 v[144:145], v[26:27], s[60:61], v[50:51] op_sel_hi:[1,0,0]
	v_pk_fma_f32 v[130:131], v[24:25], s[60:61], v[50:51] op_sel_hi:[1,0,0]
	v_pk_fma_f32 v[132:133], v[22:23], s[60:61], v[50:51] op_sel_hi:[1,0,0]
	v_pk_fma_f32 v[134:135], v[20:21], s[60:61], v[50:51] op_sel_hi:[1,0,0]
	v_pk_fma_f32 v[140:141], v[18:19], s[60:61], v[50:51] op_sel_hi:[1,0,0]
	v_pk_fma_f32 v[142:143], v[16:17], s[60:61], v[50:51] op_sel_hi:[1,0,0]
	v_cmp_gt_u32_e64 s[12:13], 32, v52
	v_add_u32_e32 v169, s20, v53
	v_mov_b64_e32 v[30:31], v[14:15]
	v_mov_b64_e32 v[46:47], v[14:15]
	v_mov_b64_e32 v[62:63], v[14:15]
	v_mov_b64_e32 v[28:29], v[12:13]
	v_mov_b64_e32 v[26:27], v[10:11]
	v_mov_b64_e32 v[24:25], v[8:9]
	v_mov_b64_e32 v[22:23], v[6:7]
	v_mov_b64_e32 v[20:21], v[4:5]
	v_mov_b64_e32 v[18:19], v[2:3]
	v_mov_b64_e32 v[16:17], v[0:1]
	v_mov_b64_e32 v[44:45], v[12:13]
	v_mov_b64_e32 v[42:43], v[10:11]
	v_mov_b64_e32 v[40:41], v[8:9]
	v_mov_b64_e32 v[38:39], v[6:7]
	v_mov_b64_e32 v[36:37], v[4:5]
	v_mov_b64_e32 v[34:35], v[2:3]
	v_mov_b64_e32 v[32:33], v[0:1]
	v_mov_b64_e32 v[60:61], v[12:13]
	v_mov_b64_e32 v[58:59], v[10:11]
	v_mov_b64_e32 v[56:57], v[8:9]
	v_mov_b64_e32 v[54:55], v[6:7]
	v_mov_b64_e32 v[52:53], v[4:5]
	v_mov_b64_e32 v[50:51], v[2:3]
	v_mov_b64_e32 v[48:49], v[0:1]
	s_waitcnt lgkmcnt(0)
	s_barrier
